# grid barrier: early inv + single pre-clean wbl2 by 17th-from-last local arriver (K=16)
# baseline (speedup 1.0000x reference)
.LBB0_141:
	s_or_b64 exec, exec, s[8:9]
	v_cvt_f32_u32_e32 v4, v2
	s_waitcnt vmcnt(0)
	buffer_inv sc1
	v_readfirstlane_b32 s6, v3
	v_sub_u32_e32 v3, 0, v2
	v_rcp_iflag_f32_e32 v4, v4
	v_add_u32_e32 v5, s6, v1
	v_mul_f32_e32 v4, 0x4f7ffffe, v4
	v_cvt_u32_f32_e32 v4, v4
	v_mul_lo_u32 v1, v3, v4
	v_mul_hi_u32 v1, v4, v1
	v_add_u32_e32 v1, v4, v1
	v_mul_hi_u32 v1, v5, v1
	v_mul_lo_u32 v3, v1, v2
	v_sub_u32_e32 v3, v5, v3
	v_add_u32_e32 v4, 1, v1
	v_cmp_ge_u32_e32 vcc, v3, v2
	s_nop 1
	v_cndmask_b32_e32 v1, v1, v4, vcc
	v_sub_u32_e32 v4, v3, v2
	v_cndmask_b32_e32 v3, v3, v4, vcc
	v_add_u32_e32 v4, 1, v1
	v_cmp_ge_u32_e32 vcc, v3, v2
	v_add_u32_e32 v3, 1, v5
	s_nop 0
	v_cndmask_b32_e32 v1, v1, v4, vcc
	v_mul_lo_u32 v4, v2, v1
	v_add_u32_e32 v2, v4, v2
	v_add_u32_e32 v4, 16, v3
	v_cmp_eq_u32_e32 vcc, v4, v2
	s_cbranch_vccz .Lnopre_0
	buffer_wbl2 sc1

.LBB0_481:
	s_or_b64 exec, exec, s[16:17]
	v_cvt_f32_u32_e32 v4, v2
	s_waitcnt vmcnt(0)
	buffer_inv sc1
	v_readfirstlane_b32 s6, v3
	v_sub_u32_e32 v3, 0, v2
	v_rcp_iflag_f32_e32 v4, v4
	v_add_u32_e32 v5, s6, v1
	v_mul_f32_e32 v4, 0x4f7ffffe, v4
	v_cvt_u32_f32_e32 v4, v4
	v_mul_lo_u32 v1, v3, v4
	v_mul_hi_u32 v1, v4, v1
	v_add_u32_e32 v1, v4, v1
	v_mul_hi_u32 v1, v5, v1
	v_mul_lo_u32 v3, v1, v2
	v_sub_u32_e32 v3, v5, v3
	v_add_u32_e32 v4, 1, v1
	v_cmp_ge_u32_e32 vcc, v3, v2
	s_nop 1
	v_cndmask_b32_e32 v1, v1, v4, vcc
	v_sub_u32_e32 v4, v3, v2
	v_cndmask_b32_e32 v3, v3, v4, vcc
	v_add_u32_e32 v4, 1, v1
	v_cmp_ge_u32_e32 vcc, v3, v2
	v_add_u32_e32 v3, 1, v5
	s_nop 0
	v_cndmask_b32_e32 v1, v1, v4, vcc
	v_mul_lo_u32 v4, v2, v1
	v_add_u32_e32 v2, v4, v2
	v_add_u32_e32 v4, 16, v3
	v_cmp_eq_u32_e32 vcc, v4, v2
	s_cbranch_vccz .Lnopre_5
	buffer_wbl2 sc1

.LBB0_626:
	s_or_b64 exec, exec, s[10:11]
	v_cvt_f32_u32_e32 v4, v2
	s_waitcnt vmcnt(0)
	buffer_inv sc1
	v_readfirstlane_b32 s8, v3
	v_sub_u32_e32 v3, 0, v2
	v_rcp_iflag_f32_e32 v4, v4
	v_add_u32_e32 v5, s8, v1
	v_mul_f32_e32 v4, 0x4f7ffffe, v4
	v_cvt_u32_f32_e32 v4, v4
	v_mul_lo_u32 v1, v3, v4
	v_mul_hi_u32 v1, v4, v1
	v_add_u32_e32 v1, v4, v1
	v_mul_hi_u32 v1, v5, v1
	v_mul_lo_u32 v3, v1, v2
	v_sub_u32_e32 v3, v5, v3
	v_add_u32_e32 v4, 1, v1
	v_cmp_ge_u32_e32 vcc, v3, v2
	s_nop 1
	v_cndmask_b32_e32 v1, v1, v4, vcc
	v_sub_u32_e32 v4, v3, v2
	v_cndmask_b32_e32 v3, v3, v4, vcc
	v_add_u32_e32 v4, 1, v1
	v_cmp_ge_u32_e32 vcc, v3, v2
	v_add_u32_e32 v3, 1, v5
	s_nop 0
	v_cndmask_b32_e32 v1, v1, v4, vcc
	v_mul_lo_u32 v4, v2, v1
	v_add_u32_e32 v2, v4, v2
	v_add_u32_e32 v4, 16, v3
	v_cmp_eq_u32_e32 vcc, v4, v2
	s_cbranch_vccz .Lnopre_7
	buffer_wbl2 sc1

.LBB0_681:
	s_or_b64 exec, exec, s[12:13]
	v_cvt_f32_u32_e32 v4, v2
	s_waitcnt vmcnt(0)
	buffer_inv sc1
	v_readfirstlane_b32 s10, v3
	v_sub_u32_e32 v3, 0, v2
	v_rcp_iflag_f32_e32 v4, v4
	v_add_u32_e32 v5, s10, v1
	v_mul_f32_e32 v4, 0x4f7ffffe, v4
	v_cvt_u32_f32_e32 v4, v4
	v_mul_lo_u32 v1, v3, v4
	v_mul_hi_u32 v1, v4, v1
	v_add_u32_e32 v1, v4, v1
	v_mul_hi_u32 v1, v5, v1
	v_mul_lo_u32 v3, v1, v2
	v_sub_u32_e32 v3, v5, v3
	v_add_u32_e32 v4, 1, v1
	v_cmp_ge_u32_e32 vcc, v3, v2
	s_nop 1
	v_cndmask_b32_e32 v1, v1, v4, vcc
	v_sub_u32_e32 v4, v3, v2
	v_cndmask_b32_e32 v3, v3, v4, vcc
	v_add_u32_e32 v4, 1, v1
	v_cmp_ge_u32_e32 vcc, v3, v2
	v_add_u32_e32 v3, 1, v5
	s_nop 0
	v_cndmask_b32_e32 v1, v1, v4, vcc
	v_mul_lo_u32 v4, v2, v1
	v_add_u32_e32 v2, v4, v2
	v_add_u32_e32 v4, 16, v3
	v_cmp_eq_u32_e32 vcc, v4, v2
	s_cbranch_vccz .Lnopre_8
	buffer_wbl2 sc1

.LBB0_749:
	s_or_b64 exec, exec, s[16:17]
	v_cvt_f32_u32_e32 v4, v2
	s_waitcnt vmcnt(0)
	buffer_inv sc1
	v_readfirstlane_b32 s12, v3
	v_sub_u32_e32 v3, 0, v2
	v_rcp_iflag_f32_e32 v4, v4
	v_add_u32_e32 v5, s12, v1
	v_mul_f32_e32 v4, 0x4f7ffffe, v4
	v_cvt_u32_f32_e32 v4, v4
	v_mul_lo_u32 v1, v3, v4
	v_mul_hi_u32 v1, v4, v1
	v_add_u32_e32 v1, v4, v1
	v_mul_hi_u32 v1, v5, v1
	v_mul_lo_u32 v3, v1, v2
	v_sub_u32_e32 v3, v5, v3
	v_add_u32_e32 v4, 1, v1
	v_cmp_ge_u32_e32 vcc, v3, v2
	s_nop 1
	v_cndmask_b32_e32 v1, v1, v4, vcc
	v_sub_u32_e32 v4, v3, v2
	v_cndmask_b32_e32 v3, v3, v4, vcc
	v_add_u32_e32 v4, 1, v1
	v_cmp_ge_u32_e32 vcc, v3, v2
	v_add_u32_e32 v3, 1, v5
	s_nop 0
	v_cndmask_b32_e32 v1, v1, v4, vcc
	v_mul_lo_u32 v4, v2, v1
	v_add_u32_e32 v2, v4, v2
	v_add_u32_e32 v4, 16, v3
	v_cmp_eq_u32_e32 vcc, v4, v2
	s_cbranch_vccz .Lnopre_9
	buffer_wbl2 sc1
